# adds drained-list skip in attention work queue and two-pass DPP attention-group norm in LRU pass2
# baseline (speedup 1.0000x reference)
.LBB0_290:
	v_add_u32_e32 v5, s6, v0
	ds_read2st64_b32 v[8:9], v5 offset1:1
	ds_read2st64_b32 v[12:13], v6 offset1:1
	ds_read2st64_b32 v[14:15], v6 offset0:2 offset1:3
	s_add_i32 s6, s6, 64
	s_cmpk_lg_i32 s6, 0x100
	s_waitcnt lgkmcnt(2)
	v_add_f32_e32 v7, 0, v8
	v_add_f32_e32 v7, v7, v9
	ds_read2st64_b32 v[8:9], v5 offset0:2 offset1:3
	s_waitcnt lgkmcnt(0)
	v_add_f32_e32 v7, v7, v8
	v_add_f32_e32 v7, v7, v9
	ds_read2st64_b32 v[8:9], v5 offset0:4 offset1:5
	s_waitcnt lgkmcnt(0)
	v_add_f32_e32 v7, v7, v8
	v_add_f32_e32 v7, v7, v9
	ds_read2st64_b32 v[8:9], v5 offset0:6 offset1:7
	s_waitcnt lgkmcnt(0)
	v_add_f32_e32 v5, v7, v8
	v_add_f32_e32 v5, v5, v9
	v_fmamk_f32 v5, v5, 0x3b000000, v190
	v_cmp_gt_f32_e32 vcc, s96, v5
	v_mul_f32_e32 v7, 0x4b800000, v5
	s_nop 0
	v_cndmask_b32_e32 v5, v5, v7, vcc
	v_rsq_f32_e32 v5, v5
	s_nop 0
	v_mul_f32_e32 v7, 0x45800000, v5
	v_cndmask_b32_e32 v8, v5, v7, vcc
	v_ashrrev_i32_e32 v5, 31, v4
	v_lshlrev_b64 v[10:11], 11, v[4:5]
	v_pk_mul_f32 v[12:13], v[12:13], v[8:9] op_sel_hi:[1,0]
	v_pk_mul_f32 v[14:15], v[14:15], v[8:9] op_sel_hi:[1,0]
	v_lshl_add_u64 v[10:11], v[2:3], 0, v[10:11]
	v_cvt_pk_bf16_f32 v12, v12, v13
	v_cvt_pk_bf16_f32 v13, v14, v15
	global_store_dwordx2 v[10:11], v[12:13], off offset:1024
	ds_read2st64_b32 v[12:13], v6 offset0:4 offset1:5
	ds_read2st64_b32 v[14:15], v6 offset0:6 offset1:7
	v_add_u32_e32 v4, 16, v4
	s_waitcnt lgkmcnt(1)
	v_pk_mul_f32 v[12:13], v[12:13], v[8:9] op_sel_hi:[1,0]
	s_waitcnt lgkmcnt(0)
	v_pk_mul_f32 v[14:15], v[8:9], v[14:15] op_sel_hi:[0,1]
	v_cvt_pk_bf16_f32 v12, v12, v13
	v_cvt_pk_bf16_f32 v13, v14, v15
	global_store_dwordx2 v[10:11], v[12:13], off offset:1056
	ds_read2st64_b32 v[12:13], v6 offset0:8 offset1:9
	ds_read2st64_b32 v[14:15], v6 offset0:10 offset1:11
	s_waitcnt lgkmcnt(1)
	v_pk_mul_f32 v[12:13], v[8:9], v[12:13] op_sel_hi:[0,1]
	s_waitcnt lgkmcnt(0)
	v_pk_mul_f32 v[14:15], v[8:9], v[14:15] op_sel_hi:[0,1]
	v_cvt_pk_bf16_f32 v12, v12, v13
	v_cvt_pk_bf16_f32 v13, v14, v15
	global_store_dwordx2 v[10:11], v[12:13], off offset:1088
	ds_read2st64_b32 v[12:13], v6 offset0:12 offset1:13
	ds_read2st64_b32 v[14:15], v6 offset0:14 offset1:15
	v_add_u32_e32 v6, 0x1000, v6
	s_waitcnt lgkmcnt(1)
	v_pk_mul_f32 v[12:13], v[8:9], v[12:13] op_sel_hi:[0,1]
	s_waitcnt lgkmcnt(0)
	v_pk_mul_f32 v[8:9], v[8:9], v[14:15] op_sel_hi:[0,1]
	v_cvt_pk_bf16_f32 v12, v12, v13
	v_cvt_pk_bf16_f32 v13, v8, v9
	global_store_dwordx2 v[10:11], v[12:13], off offset:1120
	s_cbranch_scc1 .LBB0_290
	s_add_i32 s6, s10, s43
	s_ashr_i32 s7, s6, 31
	s_lshl_b64 s[8:9], s[6:7], 10
	v_readlane_b32 s10, v255, 54
	v_lshrrev_b32_e32 v2, 4, v228
	v_and_b32_e32 v3, 15, v228
	s_add_u32 s8, s10, s8
	v_readlane_b32 s10, v255, 55
	v_lshlrev_b32_e32 v3, 6, v3
	s_addc_u32 s9, s10, s9
	s_lshl_b64 s[6:7], s[6:7], 11
	v_lshl_add_u32 v4, v2, 10, v3
	v_lshl_add_u32 v5, v2, 11, v3
	s_add_u32 s6, s33, s6
	s_addc_u32 s7, s42, s7
	v_add_u32_e32 v6, 0x1000, v4
	v_add_u32_e32 v7, 0x2000, v5
	global_load_dwordx4 v[8:11], v4, s[8:9]
	global_load_dwordx4 v[12:15], v4, s[8:9] offset:16
	global_load_dwordx4 v[16:19], v4, s[8:9] offset:32
	global_load_dwordx4 v[20:23], v4, s[8:9] offset:48
	global_load_dwordx4 v[24:27], v6, s[8:9]
	global_load_dwordx4 v[28:31], v6, s[8:9] offset:16
	global_load_dwordx4 v[32:35], v6, s[8:9] offset:32
	global_load_dwordx4 v[36:39], v6, s[8:9] offset:48
	s_mov_b32 s10, 0xffff0000
	s_waitcnt vmcnt(4)
	v_lshlrev_b32_e32 v40, 16, v8
	v_lshlrev_b32_e32 v41, 16, v9
	v_lshlrev_b32_e32 v42, 16, v10
	v_lshlrev_b32_e32 v43, 16, v11
	v_lshlrev_b32_e32 v44, 16, v12
	v_lshlrev_b32_e32 v45, 16, v13
	v_lshlrev_b32_e32 v46, 16, v14
	v_lshlrev_b32_e32 v47, 16, v15
	v_lshlrev_b32_e32 v48, 16, v16
	v_lshlrev_b32_e32 v49, 16, v17
	v_lshlrev_b32_e32 v50, 16, v18
	v_lshlrev_b32_e32 v51, 16, v19
	v_lshlrev_b32_e32 v52, 16, v20
	v_lshlrev_b32_e32 v53, 16, v21
	v_lshlrev_b32_e32 v54, 16, v22
	v_lshlrev_b32_e32 v55, 16, v23
	v_and_b32_e32 v8, s10, v8
	v_and_b32_e32 v9, s10, v9
	v_and_b32_e32 v10, s10, v10
	v_and_b32_e32 v11, s10, v11
	v_and_b32_e32 v12, s10, v12
	v_and_b32_e32 v13, s10, v13
	v_and_b32_e32 v14, s10, v14
	v_and_b32_e32 v15, s10, v15
	v_and_b32_e32 v16, s10, v16
	v_and_b32_e32 v17, s10, v17
	v_and_b32_e32 v18, s10, v18
	v_and_b32_e32 v19, s10, v19
	v_and_b32_e32 v20, s10, v20
	v_and_b32_e32 v21, s10, v21
	v_and_b32_e32 v22, s10, v22
	v_and_b32_e32 v23, s10, v23
	v_mul_f32_e32 v72, v40, v40
	v_mul_f32_e32 v73, v41, v41
	v_mul_f32_e32 v74, v42, v42
	v_mul_f32_e32 v75, v43, v43
	v_fmac_f32_e32 v72, v8, v8
	v_fmac_f32_e32 v73, v9, v9
	v_fmac_f32_e32 v74, v10, v10
	v_fmac_f32_e32 v75, v11, v11
	v_fmac_f32_e32 v72, v44, v44
	v_fmac_f32_e32 v73, v45, v45
	v_fmac_f32_e32 v74, v46, v46
	v_fmac_f32_e32 v75, v47, v47
	v_fmac_f32_e32 v72, v48, v48
	v_fmac_f32_e32 v73, v49, v49
	v_fmac_f32_e32 v74, v50, v50
	v_fmac_f32_e32 v75, v51, v51
	v_fmac_f32_e32 v72, v52, v52
	v_fmac_f32_e32 v73, v53, v53
	v_fmac_f32_e32 v74, v54, v54
	v_fmac_f32_e32 v75, v55, v55
	v_fmac_f32_e32 v72, v12, v12
	v_fmac_f32_e32 v73, v13, v13
	v_fmac_f32_e32 v74, v14, v14
	v_fmac_f32_e32 v75, v15, v15
	v_fmac_f32_e32 v72, v16, v16
	v_fmac_f32_e32 v73, v17, v17
	v_fmac_f32_e32 v74, v18, v18
	v_fmac_f32_e32 v75, v19, v19
	v_fmac_f32_e32 v72, v20, v20
	v_fmac_f32_e32 v73, v21, v21
	v_fmac_f32_e32 v74, v22, v22
	v_fmac_f32_e32 v75, v23, v23
	v_add_f32_e32 v72, v72, v73
	v_add_f32_e32 v74, v74, v75
	s_nop 0
	v_add_f32_e32 v72, v72, v74
	s_waitcnt vmcnt(0)
	v_lshlrev_b32_e32 v56, 16, v24
	v_lshlrev_b32_e32 v57, 16, v25
	v_lshlrev_b32_e32 v58, 16, v26
	v_lshlrev_b32_e32 v59, 16, v27
	v_lshlrev_b32_e32 v60, 16, v28
	v_lshlrev_b32_e32 v61, 16, v29
	v_lshlrev_b32_e32 v62, 16, v30
	v_lshlrev_b32_e32 v63, 16, v31
	v_lshlrev_b32_e32 v64, 16, v32
	v_lshlrev_b32_e32 v65, 16, v33
	v_lshlrev_b32_e32 v66, 16, v34
	v_lshlrev_b32_e32 v67, 16, v35
	v_lshlrev_b32_e32 v68, 16, v36
	v_lshlrev_b32_e32 v69, 16, v37
	v_lshlrev_b32_e32 v70, 16, v38
	v_lshlrev_b32_e32 v71, 16, v39
	v_and_b32_e32 v24, s10, v24
	v_and_b32_e32 v25, s10, v25
	v_and_b32_e32 v26, s10, v26
	v_and_b32_e32 v27, s10, v27
	v_and_b32_e32 v28, s10, v28
	v_and_b32_e32 v29, s10, v29
	v_and_b32_e32 v30, s10, v30
	v_and_b32_e32 v31, s10, v31
	v_and_b32_e32 v32, s10, v32
	v_and_b32_e32 v33, s10, v33
	v_and_b32_e32 v34, s10, v34
	v_and_b32_e32 v35, s10, v35
	v_and_b32_e32 v36, s10, v36
	v_and_b32_e32 v37, s10, v37
	v_and_b32_e32 v38, s10, v38
	v_and_b32_e32 v39, s10, v39
	v_mul_f32_e32 v76, v56, v56
	v_mul_f32_e32 v77, v57, v57
	v_mul_f32_e32 v78, v58, v58
	v_mul_f32_e32 v79, v59, v59
	v_fmac_f32_e32 v76, v24, v24
	v_fmac_f32_e32 v77, v25, v25
	v_fmac_f32_e32 v78, v26, v26
	v_fmac_f32_e32 v79, v27, v27
	v_fmac_f32_e32 v76, v60, v60
	v_fmac_f32_e32 v77, v61, v61
	v_fmac_f32_e32 v78, v62, v62
	v_fmac_f32_e32 v79, v63, v63
	v_fmac_f32_e32 v76, v64, v64
	v_fmac_f32_e32 v77, v65, v65
	v_fmac_f32_e32 v78, v66, v66
	v_fmac_f32_e32 v79, v67, v67
	v_fmac_f32_e32 v76, v68, v68
	v_fmac_f32_e32 v77, v69, v69
	v_fmac_f32_e32 v78, v70, v70
	v_fmac_f32_e32 v79, v71, v71
	v_fmac_f32_e32 v76, v28, v28
	v_fmac_f32_e32 v77, v29, v29
	v_fmac_f32_e32 v78, v30, v30
	v_fmac_f32_e32 v79, v31, v31
	v_fmac_f32_e32 v76, v32, v32
	v_fmac_f32_e32 v77, v33, v33
	v_fmac_f32_e32 v78, v34, v34
	v_fmac_f32_e32 v79, v35, v35
	v_fmac_f32_e32 v76, v36, v36
	v_fmac_f32_e32 v77, v37, v37
	v_fmac_f32_e32 v78, v38, v38
	v_fmac_f32_e32 v79, v39, v39
	v_add_f32_e32 v76, v76, v77
	v_add_f32_e32 v78, v78, v79
	s_nop 0
	v_add_f32_e32 v76, v76, v78
	s_nop 1
	v_add_f32_dpp v73, v72, v72 quad_perm:[1,0,3,2] row_mask:0xf bank_mask:0xf
	v_add_f32_dpp v77, v76, v76 quad_perm:[1,0,3,2] row_mask:0xf bank_mask:0xf
	s_nop 0
	v_add_f32_dpp v72, v73, v73 quad_perm:[2,3,0,1] row_mask:0xf bank_mask:0xf
	v_add_f32_dpp v76, v77, v77 quad_perm:[2,3,0,1] row_mask:0xf bank_mask:0xf
	s_nop 0
	v_add_f32_dpp v73, v72, v72 row_half_mirror row_mask:0xf bank_mask:0xf
	v_add_f32_dpp v77, v76, v76 row_half_mirror row_mask:0xf bank_mask:0xf
	s_nop 0
	v_add_f32_dpp v72, v73, v73 row_mirror row_mask:0xf bank_mask:0xf
	v_add_f32_dpp v76, v77, v77 row_mirror row_mask:0xf bank_mask:0xf
	s_nop 0
	v_fmamk_f32 v72, v72, 0x3b000000, v190
	v_fmamk_f32 v76, v76, 0x3b000000, v190
	v_cmp_gt_f32_e32 vcc, s96, v72
	v_cmp_gt_f32_e64 s[8:9], s96, v76
	v_mul_f32_e32 v73, 0x4b800000, v72
	v_mul_f32_e32 v77, 0x4b800000, v76
	v_cndmask_b32_e32 v72, v72, v73, vcc
	v_cndmask_b32_e64 v76, v76, v77, s[8:9]
	v_rsq_f32_e32 v72, v72
	v_rsq_f32_e32 v76, v76
	s_nop 0
	v_mul_f32_e32 v73, 0x45800000, v72
	v_mul_f32_e32 v77, 0x45800000, v76
	v_cndmask_b32_e32 v72, v72, v73, vcc
	v_cndmask_b32_e64 v76, v76, v77, s[8:9]
	v_mul_f32_e32 v40, v72, v40
	v_mul_f32_e32 v41, v72, v41
	v_mul_f32_e32 v42, v72, v42
	v_mul_f32_e32 v43, v72, v43
	v_mul_f32_e32 v44, v72, v44
	v_mul_f32_e32 v45, v72, v45
	v_mul_f32_e32 v46, v72, v46
	v_mul_f32_e32 v47, v72, v47
	v_mul_f32_e32 v48, v72, v48
	v_mul_f32_e32 v49, v72, v49
	v_mul_f32_e32 v50, v72, v50
	v_mul_f32_e32 v51, v72, v51
	v_mul_f32_e32 v52, v72, v52
	v_mul_f32_e32 v53, v72, v53
	v_mul_f32_e32 v54, v72, v54
	v_mul_f32_e32 v55, v72, v55
	v_mul_f32_e32 v8, v72, v8
	v_mul_f32_e32 v9, v72, v9
	v_mul_f32_e32 v10, v72, v10
	v_mul_f32_e32 v11, v72, v11
	v_mul_f32_e32 v12, v72, v12
	v_mul_f32_e32 v13, v72, v13
	v_mul_f32_e32 v14, v72, v14
	v_mul_f32_e32 v15, v72, v15
	v_mul_f32_e32 v16, v72, v16
	v_mul_f32_e32 v17, v72, v17
	v_mul_f32_e32 v18, v72, v18
	v_mul_f32_e32 v19, v72, v19
	v_mul_f32_e32 v20, v72, v20
	v_mul_f32_e32 v21, v72, v21
	v_mul_f32_e32 v22, v72, v22
	v_mul_f32_e32 v23, v72, v23
	v_cvt_pk_bf16_f32 v8, v40, v8
	v_cvt_pk_bf16_f32 v9, v41, v9
	v_cvt_pk_bf16_f32 v10, v42, v10
	v_cvt_pk_bf16_f32 v11, v43, v11
	v_cvt_pk_bf16_f32 v12, v44, v12
	v_cvt_pk_bf16_f32 v13, v45, v13
	v_cvt_pk_bf16_f32 v14, v46, v14
	v_cvt_pk_bf16_f32 v15, v47, v15
	v_cvt_pk_bf16_f32 v16, v48, v16
	v_cvt_pk_bf16_f32 v17, v49, v17
	v_cvt_pk_bf16_f32 v18, v50, v18
	v_cvt_pk_bf16_f32 v19, v51, v19
	v_cvt_pk_bf16_f32 v20, v52, v20
	v_cvt_pk_bf16_f32 v21, v53, v21
	v_cvt_pk_bf16_f32 v22, v54, v22
	v_cvt_pk_bf16_f32 v23, v55, v23
	v_mul_f32_e32 v56, v76, v56
	v_mul_f32_e32 v57, v76, v57
	v_mul_f32_e32 v58, v76, v58
	v_mul_f32_e32 v59, v76, v59
	v_mul_f32_e32 v60, v76, v60
	v_mul_f32_e32 v61, v76, v61
	v_mul_f32_e32 v62, v76, v62
	v_mul_f32_e32 v63, v76, v63
	v_mul_f32_e32 v64, v76, v64
	v_mul_f32_e32 v65, v76, v65
	v_mul_f32_e32 v66, v76, v66
	v_mul_f32_e32 v67, v76, v67
	v_mul_f32_e32 v68, v76, v68
	v_mul_f32_e32 v69, v76, v69
	v_mul_f32_e32 v70, v76, v70
	v_mul_f32_e32 v71, v76, v71
	v_mul_f32_e32 v24, v76, v24
	v_mul_f32_e32 v25, v76, v25
	v_mul_f32_e32 v26, v76, v26
	v_mul_f32_e32 v27, v76, v27
	v_mul_f32_e32 v28, v76, v28
	v_mul_f32_e32 v29, v76, v29
	v_mul_f32_e32 v30, v76, v30
	v_mul_f32_e32 v31, v76, v31
	v_mul_f32_e32 v32, v76, v32
	v_mul_f32_e32 v33, v76, v33
	v_mul_f32_e32 v34, v76, v34
	v_mul_f32_e32 v35, v76, v35
	v_mul_f32_e32 v36, v76, v36
	v_mul_f32_e32 v37, v76, v37
	v_mul_f32_e32 v38, v76, v38
	v_mul_f32_e32 v39, v76, v39
	v_cvt_pk_bf16_f32 v24, v56, v24
	v_cvt_pk_bf16_f32 v25, v57, v25
	v_cvt_pk_bf16_f32 v26, v58, v26
	v_cvt_pk_bf16_f32 v27, v59, v27
	v_cvt_pk_bf16_f32 v28, v60, v28
	v_cvt_pk_bf16_f32 v29, v61, v29
	v_cvt_pk_bf16_f32 v30, v62, v30
	v_cvt_pk_bf16_f32 v31, v63, v31
	v_cvt_pk_bf16_f32 v32, v64, v32
	v_cvt_pk_bf16_f32 v33, v65, v33
	v_cvt_pk_bf16_f32 v34, v66, v34
	v_cvt_pk_bf16_f32 v35, v67, v35
	v_cvt_pk_bf16_f32 v36, v68, v36
	v_cvt_pk_bf16_f32 v37, v69, v37
	v_cvt_pk_bf16_f32 v38, v70, v38
	v_cvt_pk_bf16_f32 v39, v71, v39
	global_store_dwordx4 v5, v[8:11], s[6:7]
	global_store_dwordx4 v5, v[12:15], s[6:7] offset:16
	global_store_dwordx4 v5, v[16:19], s[6:7] offset:32
	global_store_dwordx4 v5, v[20:23], s[6:7] offset:48
	global_store_dwordx4 v7, v[24:27], s[6:7]
	global_store_dwordx4 v7, v[28:31], s[6:7] offset:16
	global_store_dwordx4 v7, v[32:35], s[6:7] offset:32
	global_store_dwordx4 v7, v[36:39], s[6:7] offset:48
	s_waitcnt lgkmcnt(0)
	s_add_i32 s57, s57, s81
	v_readlane_b32 s6, v255, 31
	s_cmp_ge_i32 s57, s6
	s_barrier
	s_cbranch_scc0 .LBB0_268

.LBB0_322:
	s_add_i32 s79, s79, 1
	s_cmp_eq_u32 s79, 8
	s_cbranch_scc1 .LBB0_419
	s_cmp_lg_u32 s79, 1
	s_cbranch_scc1 .Lq_mask_ready
	s_cmp_lg_u64 s[6:7], 0
	s_cbranch_scc0 .Lq_skipload
	s_mov_b64 s[8:9], exec
	s_mov_b64 exec, 0xff
	v_lshlrev_b32_e32 v2, 8, v228
	v_readlane_b32 s10, v255, 62
	v_readlane_b32 s11, v255, 63
	s_nop 4
	global_load_dword v3, v2, s[10:11] sc1
	s_waitcnt vmcnt(0)
	v_cmp_le_i32_e32 vcc, s2, v3
	s_mov_b64 exec, s[8:9]
	s_nop 1
	v_mov_b32_e32 v2, vcc_lo
	v_mov_b32_e32 v3, s61
	ds_write_b32 v3, v2
.Lq_skipload:
	s_waitcnt lgkmcnt(0)
	s_barrier
	v_mov_b32_e32 v0, s61
	ds_read_b32 v0, v0
	s_waitcnt lgkmcnt(0)
	v_readfirstlane_b32 s100, v0
.Lq_mask_ready:
	v_readlane_b32 s3, v255, 56
	s_add_i32 s3, s79, s3
	s_and_b32 s3, s3, 7
	s_bitcmp1_b32 s100, s3
	s_cbranch_scc1 .LBB0_322

	.amdhsa_kernel _Z4mega4Args
		.amdhsa_group_segment_fixed_size 0
		.amdhsa_private_segment_fixed_size 0
		.amdhsa_kernarg_size 472
		.amdhsa_user_sgpr_count 2
		.amdhsa_user_sgpr_dispatch_ptr 0
		.amdhsa_user_sgpr_queue_ptr 0
		.amdhsa_user_sgpr_kernarg_segment_ptr 1
		.amdhsa_user_sgpr_dispatch_id 0
		.amdhsa_user_sgpr_kernarg_preload_length 0
		.amdhsa_user_sgpr_kernarg_preload_offset 0
		.amdhsa_user_sgpr_private_segment_size 0
		.amdhsa_uses_dynamic_stack 0
		.amdhsa_enable_private_segment 0
		.amdhsa_system_sgpr_workgroup_id_x 1
		.amdhsa_system_sgpr_workgroup_id_y 0
		.amdhsa_system_sgpr_workgroup_id_z 0
		.amdhsa_system_sgpr_workgroup_info 0
		.amdhsa_system_vgpr_workitem_id 2
		.amdhsa_next_free_vgpr 256
		.amdhsa_next_free_sgpr 101
		.amdhsa_accum_offset 256
		.amdhsa_reserve_vcc 1
		.amdhsa_float_round_mode_32 0
		.amdhsa_float_round_mode_16_64 0
		.amdhsa_float_denorm_mode_32 3
		.amdhsa_float_denorm_mode_16_64 3
		.amdhsa_dx10_clamp 1
		.amdhsa_ieee_mode 1
		.amdhsa_fp16_overflow 0
		.amdhsa_tg_split 0
		.amdhsa_exception_fp_ieee_invalid_op 0
		.amdhsa_exception_fp_denorm_src 0
		.amdhsa_exception_fp_ieee_div_zero 0
		.amdhsa_exception_fp_ieee_overflow 0
		.amdhsa_exception_fp_ieee_underflow 0
		.amdhsa_exception_fp_ieee_inexact 0
		.amdhsa_exception_int_div_zero 0
	.end_amdhsa_kernel

amdhsa.kernels:
  - .agpr_count:     0
    .args:
      - .offset:         0
        .size:           216
        .value_kind:     by_value
      - .offset:         216
        .size:           4
        .value_kind:     hidden_block_count_x
      - .offset:         220
        .size:           4
        .value_kind:     hidden_block_count_y
      - .offset:         224
        .size:           4
        .value_kind:     hidden_block_count_z
      - .offset:         228
        .size:           2
        .value_kind:     hidden_group_size_x
      - .offset:         230
        .size:           2
        .value_kind:     hidden_group_size_y
      - .offset:         232
        .size:           2
        .value_kind:     hidden_group_size_z
      - .offset:         234
        .size:           2
        .value_kind:     hidden_remainder_x
      - .offset:         236
        .size:           2
        .value_kind:     hidden_remainder_y
      - .offset:         238
        .size:           2
        .value_kind:     hidden_remainder_z
      - .offset:         256
        .size:           8
        .value_kind:     hidden_global_offset_x
      - .offset:         264
        .size:           8
        .value_kind:     hidden_global_offset_y
      - .offset:         272
        .size:           8
        .value_kind:     hidden_global_offset_z
      - .offset:         280
        .size:           2
        .value_kind:     hidden_grid_dims
      - .offset:         304
        .size:           8
        .value_kind:     hidden_multigrid_sync_arg
      - .offset:         336
        .size:           4
        .value_kind:     hidden_dynamic_lds_size
    .group_segment_fixed_size: 0
    .kernarg_segment_align: 8
    .kernarg_segment_size: 472
    .language:       OpenCL C
    .language_version:
      - 2
      - 0
    .max_flat_workgroup_size: 512
    .name:           _Z4mega4Args
    .private_segment_fixed_size: 0
    .sgpr_count:     107
    .sgpr_spill_count: 136
    .symbol:         _Z4mega4Args.kd
    .uniform_work_group_size: 1
    .uses_dynamic_stack: false
    .vgpr_count:     256
    .vgpr_spill_count: 0
    .wavefront_size: 64
